# v16: v14 plus single-batch ssq prefetch in the FFN-up epilogue and two-ahead gain loads in the diff-attention unit tail
# speedup vs baseline: 1.0077x; 1.0018x over previous
; DI void diff_attn_unit(int b, int h, int qb, const bf16_t* Z, const bf16_t* VT, bf16_t* H, float lam, const float* subg, float oscale, LAS unsigned char* lds, int wid, int lane) {
;     ...
;     __syncthreads();
;     if (mp == 0) { const float i0 = 1.0f / ls; float ss = 0.f;
; #pragma unroll
;         for (int d = 0; d < 4; ++d)
; #pragma unroll
;             for (int i = 0; i < 16; ++i) { const float o = O[d][i] * i0 - xch[(d * 16 + i) * 64 + lane]; O[d][i] = o; ss += o * o; }
.LBB0_2225:
	v_cndmask_b32_e64 v65, 0, 1, s[40:41]
	v_cmp_ne_u32_e64 s[2:3], 1, v65
	s_andn2_b64 vcc, exec, s[40:41]
	v_lshlrev_b32_e32 v138, 1, v116
	s_waitcnt lgkmcnt(0)
	s_barrier
	s_cbranch_vccnz .LBB0_2227
	v_div_scale_f32 v65, s[4:5], v64, v64, 1.0
	v_rcp_f32_e32 v66, v65
	s_lshl_b32 s6, s54, 1
	v_mov_b32_e32 v139, v97
	v_fma_f32 v67, -v65, v66, 1.0
	v_fmac_f32_e32 v66, v67, v66
	v_div_scale_f32 v67, vcc, 1.0, v64, 1.0
	v_mul_f32_e32 v68, v67, v66
	v_fma_f32 v69, -v65, v68, v67
	v_fmac_f32_e32 v68, v69, v66
	v_fma_f32 v65, -v65, v68, v67
	v_div_fmas_f32 v65, v65, v66, v68
	v_div_fixup_f32 v68, v65, v64, 1.0
	ds_read2st64_b32 v[80:81], v188 offset1:1
	ds_read2st64_b32 v[76:77], v188 offset0:2 offset1:3
	ds_read2st64_b32 v[94:95], v188 offset0:4 offset1:5
	ds_read2st64_b32 v[86:87], v188 offset0:6 offset1:7
	ds_read2st64_b32 v[98:99], v188 offset0:8 offset1:9
	ds_read2st64_b32 v[150:151], v188 offset0:10 offset1:11
	ds_read2st64_b32 v[152:153], v188 offset0:12 offset1:13
	ds_read2st64_b32 v[192:193], v188 offset0:14 offset1:15
	ds_read2st64_b32 v[194:195], v188 offset0:16 offset1:17
	ds_read2st64_b32 v[196:197], v188 offset0:18 offset1:19
	ds_read2st64_b32 v[198:199], v188 offset0:20 offset1:21
	ds_read2st64_b32 v[200:201], v188 offset0:22 offset1:23
	ds_read2st64_b32 v[166:167], v188 offset0:24 offset1:25
	ds_read2st64_b32 v[202:203], v188 offset0:26 offset1:27
	ds_read2st64_b32 v[162:163], v188 offset0:28 offset1:29
	ds_read2st64_b32 v[168:169], v188 offset0:30 offset1:31
	ds_read2st64_b32 v[108:109], v188 offset0:32 offset1:33
	ds_read2st64_b32 v[164:165], v188 offset0:34 offset1:35
	ds_read2st64_b32 v[104:105], v188 offset0:36 offset1:37
	ds_read2st64_b32 v[110:111], v188 offset0:38 offset1:39
	ds_read2st64_b32 v[100:101], v188 offset0:40 offset1:41
	ds_read2st64_b32 v[106:107], v188 offset0:42 offset1:43
	ds_read2st64_b32 v[92:93], v188 offset0:44 offset1:45
	ds_read2st64_b32 v[102:103], v188 offset0:46 offset1:47
	ds_read2st64_b32 v[88:89], v188 offset0:48 offset1:49
	ds_read2st64_b32 v[90:91], v188 offset0:50 offset1:51
	ds_read2st64_b32 v[78:79], v188 offset0:52 offset1:53
	ds_read2st64_b32 v[84:85], v188 offset0:54 offset1:55
	ds_read2st64_b32 v[72:73], v188 offset0:56 offset1:57
	ds_read2st64_b32 v[64:65], v188 offset0:58 offset1:59
	s_waitcnt lgkmcnt(14)
	v_pk_fma_f32 v[82:83], v[48:49], v[68:69], v[80:81] op_sel_hi:[1,0,1] neg_lo:[0,0,1] neg_hi:[0,0,1]
	v_pk_fma_f32 v[76:77], v[50:51], v[68:69], v[76:77] op_sel_hi:[1,0,1] neg_lo:[0,0,1] neg_hi:[0,0,1]
	v_pk_mul_f32 v[210:211], v[82:83], v[82:83]
	v_pk_mul_f32 v[204:205], v[76:77], v[76:77]
	s_waitcnt lgkmcnt(0)
	v_pk_fma_f32 v[64:65], v[10:11], v[68:69], v[64:65] op_sel_hi:[1,0,1] neg_lo:[0,0,1] neg_hi:[0,0,1]
	ds_read2st64_b32 v[10:11], v188 offset0:60 offset1:61
	v_pk_fma_f32 v[86:87], v[54:55], v[68:69], v[86:87] op_sel_hi:[1,0,1] neg_lo:[0,0,1] neg_hi:[0,0,1]
	v_pk_fma_f32 v[94:95], v[52:53], v[68:69], v[94:95] op_sel_hi:[1,0,1] neg_lo:[0,0,1] neg_hi:[0,0,1]
	v_pk_fma_f32 v[80:81], v[58:59], v[68:69], v[150:151] op_sel_hi:[1,0,1] neg_lo:[0,0,1] neg_hi:[0,0,1]
	v_pk_fma_f32 v[98:99], v[56:57], v[68:69], v[98:99] op_sel_hi:[1,0,1] neg_lo:[0,0,1] neg_hi:[0,0,1]
	s_waitcnt lgkmcnt(0)
	v_pk_fma_f32 v[66:67], v[12:13], v[68:69], v[10:11] op_sel_hi:[1,0,1] neg_lo:[0,0,1] neg_hi:[0,0,1]
	ds_read2st64_b32 v[10:11], v188 offset0:62 offset1:63
	v_pk_fma_f32 v[62:63], v[62:63], v[68:69], v[192:193] op_sel_hi:[1,0,1] neg_lo:[0,0,1] neg_hi:[0,0,1]
	v_pk_fma_f32 v[60:61], v[60:61], v[68:69], v[152:153] op_sel_hi:[1,0,1] neg_lo:[0,0,1] neg_hi:[0,0,1]
	v_pk_fma_f32 v[56:57], v[34:35], v[68:69], v[196:197] op_sel_hi:[1,0,1] neg_lo:[0,0,1] neg_hi:[0,0,1]
	v_pk_fma_f32 v[58:59], v[32:33], v[68:69], v[194:195] op_sel_hi:[1,0,1] neg_lo:[0,0,1] neg_hi:[0,0,1]
	s_waitcnt lgkmcnt(0)
	v_pk_fma_f32 v[14:15], v[14:15], v[68:69], v[10:11] op_sel_hi:[1,0,1] neg_lo:[0,0,1] neg_hi:[0,0,1]
	v_pk_fma_f32 v[50:51], v[38:39], v[68:69], v[200:201] op_sel_hi:[1,0,1] neg_lo:[0,0,1] neg_hi:[0,0,1]
	v_pk_fma_f32 v[54:55], v[36:37], v[68:69], v[198:199] op_sel_hi:[1,0,1] neg_lo:[0,0,1] neg_hi:[0,0,1]
	v_pk_fma_f32 v[42:43], v[42:43], v[68:69], v[202:203] op_sel_hi:[1,0,1] neg_lo:[0,0,1] neg_hi:[0,0,1]
	v_pk_fma_f32 v[52:53], v[40:41], v[68:69], v[166:167] op_sel_hi:[1,0,1] neg_lo:[0,0,1] neg_hi:[0,0,1]
	v_pk_fma_f32 v[40:41], v[46:47], v[68:69], v[168:169] op_sel_hi:[1,0,1] neg_lo:[0,0,1] neg_hi:[0,0,1]
	v_pk_fma_f32 v[44:45], v[44:45], v[68:69], v[162:163] op_sel_hi:[1,0,1] neg_lo:[0,0,1] neg_hi:[0,0,1]
	v_pk_fma_f32 v[36:37], v[18:19], v[68:69], v[164:165] op_sel_hi:[1,0,1] neg_lo:[0,0,1] neg_hi:[0,0,1]
	v_pk_fma_f32 v[38:39], v[16:17], v[68:69], v[108:109] op_sel_hi:[1,0,1] neg_lo:[0,0,1] neg_hi:[0,0,1]
	v_pk_fma_f32 v[32:33], v[22:23], v[68:69], v[110:111] op_sel_hi:[1,0,1] neg_lo:[0,0,1] neg_hi:[0,0,1]
	v_pk_fma_f32 v[34:35], v[20:21], v[68:69], v[104:105] op_sel_hi:[1,0,1] neg_lo:[0,0,1] neg_hi:[0,0,1]
	v_pk_fma_f32 v[22:23], v[26:27], v[68:69], v[106:107] op_sel_hi:[1,0,1] neg_lo:[0,0,1] neg_hi:[0,0,1]
	v_pk_fma_f32 v[26:27], v[24:25], v[68:69], v[100:101] op_sel_hi:[1,0,1] neg_lo:[0,0,1] neg_hi:[0,0,1]
	v_pk_fma_f32 v[20:21], v[30:31], v[68:69], v[102:103] op_sel_hi:[1,0,1] neg_lo:[0,0,1] neg_hi:[0,0,1]
	v_pk_fma_f32 v[24:25], v[28:29], v[68:69], v[92:93] op_sel_hi:[1,0,1] neg_lo:[0,0,1] neg_hi:[0,0,1]
	v_pk_fma_f32 v[16:17], v[2:3], v[68:69], v[90:91] op_sel_hi:[1,0,1] neg_lo:[0,0,1] neg_hi:[0,0,1]
	v_pk_fma_f32 v[18:19], v[0:1], v[68:69], v[88:89] op_sel_hi:[1,0,1] neg_lo:[0,0,1] neg_hi:[0,0,1]
	v_pk_fma_f32 v[2:3], v[6:7], v[68:69], v[84:85] op_sel_hi:[1,0,1] neg_lo:[0,0,1] neg_hi:[0,0,1]
; DI unsigned pk2(float lo, float hi) { f32x2 v = {lo, hi}; bf16x2_t b = __builtin_convertvector(v, bf16x2_t); return __builtin_bit_cast(unsigned, b); }
; DI float rstd_of(float ssq, float inv_n) { return 1.0f / sqrtf(ssq * inv_n + EPS); }
; DI void diff_attn_unit(int b, int h, int qb, const bf16_t* Z, const bf16_t* VT, bf16_t* H, float lam, const float* subg, float oscale, LAS unsigned char* lds, int wid, int lane) {
;     ...
;             for (int i = 0; i < 16; ++i) { const float o = O[d][i] * i0 - xch[(d * 16 + i) * 64 + lane]; O[d][i] = o; ss += o * o; }
;         ss += __shfl_xor(ss, 32);
;         const float rs = rstd_of(ss, 1.0f / 128.f) * oscale;
;         bf16_t* hp = H + (size_t)qrow * DM + h * 128;
; #pragma unroll
;         for (int d = 0; d < 4; ++d)
; #pragma unroll
;             for (int rg = 0; rg < 4; ++rg) { const int d0 = 32 * d + 8 * rg + 4 * hi; const f32x4 g4 = *(const f32x4*)(subg + d0);
;                 u32x2 o; o.x = pk2(O[d][4 * rg] * rs * g4[0], O[d][4 * rg + 1] * rs * g4[1]); o.y = pk2(O[d][4 * rg + 2] * rs * g4[2], O[d][4 * rg + 3] * rs * g4[3]);
;                 *(u32x2*)(hp + d0) = o; } }
	v_pk_fma_f32 v[4:5], v[4:5], v[68:69], v[78:79] op_sel_hi:[1,0,1] neg_lo:[0,0,1] neg_hi:[0,0,1]
	v_pk_fma_f32 v[0:1], v[8:9], v[68:69], v[72:73] op_sel_hi:[1,0,1] neg_lo:[0,0,1] neg_hi:[0,0,1]
	v_add_f32_e32 v68, v210, v211
	v_lshlrev_b64 v[10:11], 11, v[148:149]
	v_add_f32_e32 v68, v68, v204
	v_lshl_add_u64 v[10:11], s[48:49], 0, v[10:11]
	v_pk_mul_f32 v[212:213], v[94:95], v[94:95]
	v_add_f32_e32 v68, v68, v205
	v_lshl_add_u64 v[148:149], v[10:11], 0, s[6:7]
	v_add_f32_e32 v68, v68, v212
	v_lshl_add_u64 v[48:49], v[148:149], 0, v[138:139]
	v_pk_mul_f32 v[148:149], v[86:87], v[86:87]
	v_add_f32_e32 v68, v68, v213
	v_add_f32_e32 v68, v68, v148
	v_pk_mul_f32 v[214:215], v[98:99], v[98:99]
	v_add_f32_e32 v68, v68, v149
	v_add_f32_e32 v68, v68, v214
	v_pk_mul_f32 v[150:151], v[80:81], v[80:81]
	v_add_f32_e32 v68, v68, v215
	v_add_f32_e32 v68, v68, v150
	v_pk_mul_f32 v[152:153], v[60:61], v[60:61]
	v_add_f32_e32 v68, v68, v151
	v_add_f32_e32 v68, v68, v152
	v_pk_mul_f32 v[192:193], v[62:63], v[62:63]
	v_add_f32_e32 v68, v68, v153
	v_add_f32_e32 v68, v68, v192
	v_pk_mul_f32 v[194:195], v[58:59], v[58:59]
	v_add_f32_e32 v68, v68, v193
	v_add_f32_e32 v68, v68, v194
	v_pk_mul_f32 v[196:197], v[56:57], v[56:57]
	v_add_f32_e32 v68, v68, v195
	v_add_f32_e32 v68, v68, v196
	v_pk_mul_f32 v[198:199], v[54:55], v[54:55]
	v_add_f32_e32 v68, v68, v197
	v_add_f32_e32 v68, v68, v198
	global_load_dwordx4 v[10:13], v[118:119], off
	global_load_dwordx4 v[150:153], v[118:119], off offset:32
	global_load_dwordx4 v[192:195], v[118:119], off offset:64
	v_pk_mul_f32 v[200:201], v[50:51], v[50:51]
	v_add_f32_e32 v68, v68, v199
	v_add_f32_e32 v68, v68, v200
	v_pk_mul_f32 v[166:167], v[52:53], v[52:53]
	v_add_f32_e32 v68, v68, v201
	v_add_f32_e32 v68, v68, v166
	v_pk_mul_f32 v[202:203], v[42:43], v[42:43]
	v_add_f32_e32 v68, v68, v167
	v_add_f32_e32 v68, v68, v202
	v_pk_mul_f32 v[162:163], v[44:45], v[44:45]
	v_add_f32_e32 v68, v68, v203
	v_add_f32_e32 v68, v68, v162
	v_pk_mul_f32 v[46:47], v[40:41], v[40:41]
	v_add_f32_e32 v68, v68, v163
	v_add_f32_e32 v46, v68, v46
	v_pk_mul_f32 v[108:109], v[38:39], v[38:39]
	v_add_f32_e32 v46, v46, v47
	v_add_f32_e32 v46, v46, v108
	v_pk_mul_f32 v[164:165], v[36:37], v[36:37]
	v_add_f32_e32 v46, v46, v109
	v_add_f32_e32 v46, v46, v164
	v_pk_mul_f32 v[104:105], v[34:35], v[34:35]
	v_add_f32_e32 v46, v46, v165
	v_add_f32_e32 v46, v46, v104
	v_pk_mul_f32 v[110:111], v[32:33], v[32:33]
	v_add_f32_e32 v46, v46, v105
	v_add_f32_e32 v46, v46, v110
	v_pk_mul_f32 v[100:101], v[26:27], v[26:27]
	v_add_f32_e32 v46, v46, v111
	v_add_f32_e32 v46, v46, v100
	v_pk_mul_f32 v[106:107], v[22:23], v[22:23]
	v_add_f32_e32 v46, v46, v101
	v_add_f32_e32 v46, v46, v106
	v_pk_mul_f32 v[28:29], v[24:25], v[24:25]
	v_add_f32_e32 v46, v46, v107
	v_add_f32_e32 v28, v46, v28
	v_pk_mul_f32 v[30:31], v[20:21], v[20:21]
	v_add_f32_e32 v28, v28, v29
	v_add_f32_e32 v28, v28, v30
	v_pk_mul_f32 v[88:89], v[18:19], v[18:19]
	v_add_f32_e32 v28, v28, v31
	v_add_f32_e32 v28, v28, v88
	v_pk_mul_f32 v[90:91], v[16:17], v[16:17]
	v_add_f32_e32 v28, v28, v89
	v_add_f32_e32 v28, v28, v90
	v_pk_mul_f32 v[78:79], v[4:5], v[4:5]
	v_add_f32_e32 v28, v28, v91
	v_add_f32_e32 v28, v28, v78
	v_pk_mul_f32 v[6:7], v[2:3], v[2:3]
	v_add_f32_e32 v28, v28, v79
	v_add_f32_e32 v6, v28, v6
	v_pk_mul_f32 v[8:9], v[0:1], v[0:1]
	v_add_f32_e32 v6, v6, v7
	v_add_f32_e32 v6, v6, v8
	v_pk_mul_f32 v[70:71], v[64:65], v[64:65]
	v_add_f32_e32 v6, v6, v9
	v_add_f32_e32 v6, v6, v70
	v_pk_mul_f32 v[74:75], v[66:67], v[66:67]
	v_add_f32_e32 v6, v6, v71
	v_add_f32_e32 v6, v6, v74
	v_pk_mul_f32 v[112:113], v[14:15], v[14:15]
	v_add_f32_e32 v6, v6, v75
	v_add_f32_e32 v6, v6, v112
	v_add_f32_e32 v6, v6, v113
	ds_bpermute_b32 v7, v208, v6
	s_waitcnt lgkmcnt(0)
	v_add_f32_e32 v6, v6, v7
	v_fmamk_f32 v6, v6, 0x3c000000, v222
	v_rsq_f32_e32 v8, v6
	s_nop 0
	v_mul_f32_e32 v7, v6, v8
	v_fma_f32 v7, -v7, v8, 1.0
	v_mul_f32_e32 v7, 0.5, v7
	v_fma_f32 v6, v7, v8, v8
	v_mul_f32_e32 v6, v174, v6
	v_pk_mul_f32 v[8:9], v[82:83], v[6:7] op_sel_hi:[1,0]
	v_pk_mul_f32 v[4:5], v[4:5], v[6:7] op_sel_hi:[1,0]
	s_waitcnt vmcnt(0)
	v_pk_mul_f32 v[8:9], v[10:11], v[8:9]
	v_pk_mul_f32 v[10:11], v[76:77], v[6:7] op_sel_hi:[1,0]
	v_cvt_pk_bf16_f32 v8, v8, v9
	v_pk_mul_f32 v[10:11], v[12:13], v[10:11]
	v_pk_mul_f32 v[12:13], v[94:95], v[6:7] op_sel_hi:[1,0]
	v_cvt_pk_bf16_f32 v9, v10, v11
	global_store_dwordx2 v[48:49], v[8:9], off
	v_pk_mul_f32 v[2:3], v[2:3], v[6:7] op_sel_hi:[1,0]
	v_pk_mul_f32 v[0:1], v[0:1], v[6:7] op_sel_hi:[1,0]
	s_waitcnt vmcnt(2)
	v_mov_b64_e32 v[8:9], v[150:151]
	v_mov_b64_e32 v[10:11], v[152:153]
	global_load_dwordx4 v[150:153], v[118:119], off offset:96
	v_pk_mul_f32 v[8:9], v[8:9], v[12:13]
	v_pk_mul_f32 v[12:13], v[86:87], v[6:7] op_sel_hi:[1,0]
	v_cvt_pk_bf16_f32 v8, v8, v9
	v_pk_mul_f32 v[10:11], v[10:11], v[12:13]
	v_pk_mul_f32 v[12:13], v[98:99], v[6:7] op_sel_hi:[1,0]
	v_cvt_pk_bf16_f32 v9, v10, v11
	global_store_dwordx2 v[48:49], v[8:9], off offset:16
	s_waitcnt vmcnt(3)
	v_mov_b64_e32 v[8:9], v[192:193]
	v_mov_b64_e32 v[10:11], v[194:195]
	global_load_dwordx4 v[192:195], v[118:119], off offset:128
	v_pk_mul_f32 v[8:9], v[8:9], v[12:13]
	v_pk_mul_f32 v[12:13], v[80:81], v[6:7] op_sel_hi:[1,0]
	v_cvt_pk_bf16_f32 v8, v8, v9
	v_pk_mul_f32 v[10:11], v[10:11], v[12:13]
	v_pk_mul_f32 v[12:13], v[60:61], v[6:7] op_sel_hi:[1,0]
	v_cvt_pk_bf16_f32 v9, v10, v11
	global_store_dwordx2 v[48:49], v[8:9], off offset:32
	s_waitcnt vmcnt(3)
; DI unsigned pk2(float lo, float hi) { f32x2 v = {lo, hi}; bf16x2_t b = __builtin_convertvector(v, bf16x2_t); return __builtin_bit_cast(unsigned, b); }
; DI void diff_attn_unit(int b, int h, int qb, const bf16_t* Z, const bf16_t* VT, bf16_t* H, float lam, const float* subg, float oscale, LAS unsigned char* lds, int wid, int lane) {
;     ...
;         for (int d = 0; d < 4; ++d)
; #pragma unroll
;             for (int rg = 0; rg < 4; ++rg) { const int d0 = 32 * d + 8 * rg + 4 * hi; const f32x4 g4 = *(const f32x4*)(subg + d0);
;                 u32x2 o; o.x = pk2(O[d][4 * rg] * rs * g4[0], O[d][4 * rg + 1] * rs * g4[1]); o.y = pk2(O[d][4 * rg + 2] * rs * g4[2], O[d][4 * rg + 3] * rs * g4[3]);
;                 *(u32x2*)(hp + d0) = o; } }
	v_mov_b64_e32 v[8:9], v[150:151]
	v_mov_b64_e32 v[10:11], v[152:153]
	global_load_dwordx4 v[150:153], v[118:119], off offset:160
	v_pk_mul_f32 v[8:9], v[8:9], v[12:13]
	v_pk_mul_f32 v[12:13], v[62:63], v[6:7] op_sel_hi:[1,0]
	v_cvt_pk_bf16_f32 v8, v8, v9
	v_pk_mul_f32 v[10:11], v[10:11], v[12:13]
	v_pk_mul_f32 v[12:13], v[58:59], v[6:7] op_sel_hi:[1,0]
	v_cvt_pk_bf16_f32 v9, v10, v11
	global_store_dwordx2 v[48:49], v[8:9], off offset:48
	s_waitcnt vmcnt(3)
	v_mov_b64_e32 v[8:9], v[192:193]
	v_mov_b64_e32 v[10:11], v[194:195]
	global_load_dwordx4 v[192:195], v[118:119], off offset:192
	v_pk_mul_f32 v[8:9], v[8:9], v[12:13]
	v_pk_mul_f32 v[12:13], v[56:57], v[6:7] op_sel_hi:[1,0]
	v_cvt_pk_bf16_f32 v8, v8, v9
	v_pk_mul_f32 v[10:11], v[10:11], v[12:13]
	v_pk_mul_f32 v[12:13], v[54:55], v[6:7] op_sel_hi:[1,0]
	v_cvt_pk_bf16_f32 v9, v10, v11
	global_store_dwordx2 v[48:49], v[8:9], off offset:64
	s_waitcnt vmcnt(3)
	v_mov_b64_e32 v[8:9], v[150:151]
	v_mov_b64_e32 v[10:11], v[152:153]
	global_load_dwordx4 v[150:153], v[118:119], off offset:224
	v_pk_mul_f32 v[8:9], v[12:13], v[8:9]
	v_pk_mul_f32 v[12:13], v[50:51], v[6:7] op_sel_hi:[1,0]
	v_cvt_pk_bf16_f32 v8, v8, v9
	v_pk_mul_f32 v[10:11], v[12:13], v[10:11]
	v_pk_mul_f32 v[12:13], v[52:53], v[6:7] op_sel_hi:[1,0]
	v_cvt_pk_bf16_f32 v9, v10, v11
	global_store_dwordx2 v[48:49], v[8:9], off offset:80
	s_waitcnt vmcnt(3)
	v_mov_b64_e32 v[8:9], v[192:193]
	v_mov_b64_e32 v[10:11], v[194:195]
	global_load_dwordx4 v[192:195], v[118:119], off offset:256
	v_pk_mul_f32 v[8:9], v[12:13], v[8:9]
	v_pk_mul_f32 v[12:13], v[42:43], v[6:7] op_sel_hi:[1,0]
	v_cvt_pk_bf16_f32 v8, v8, v9
	v_pk_mul_f32 v[10:11], v[12:13], v[10:11]
	v_pk_mul_f32 v[12:13], v[44:45], v[6:7] op_sel_hi:[1,0]
	v_cvt_pk_bf16_f32 v9, v10, v11
	global_store_dwordx2 v[48:49], v[8:9], off offset:96
	s_waitcnt vmcnt(3)
	v_mov_b64_e32 v[8:9], v[150:151]
	v_mov_b64_e32 v[10:11], v[152:153]
	global_load_dwordx4 v[150:153], v[118:119], off offset:288
	v_pk_mul_f32 v[8:9], v[12:13], v[8:9]
	v_pk_mul_f32 v[12:13], v[40:41], v[6:7] op_sel_hi:[1,0]
	v_cvt_pk_bf16_f32 v8, v8, v9
	v_pk_mul_f32 v[10:11], v[12:13], v[10:11]
	v_pk_mul_f32 v[12:13], v[38:39], v[6:7] op_sel_hi:[1,0]
	v_cvt_pk_bf16_f32 v9, v10, v11
	global_store_dwordx2 v[48:49], v[8:9], off offset:112
	s_waitcnt vmcnt(3)
	v_mov_b64_e32 v[8:9], v[192:193]
	v_mov_b64_e32 v[10:11], v[194:195]
	global_load_dwordx4 v[192:195], v[118:119], off offset:320
	v_pk_mul_f32 v[8:9], v[12:13], v[8:9]
	v_pk_mul_f32 v[12:13], v[36:37], v[6:7] op_sel_hi:[1,0]
	v_cvt_pk_bf16_f32 v8, v8, v9
	v_pk_mul_f32 v[10:11], v[12:13], v[10:11]
	v_pk_mul_f32 v[12:13], v[34:35], v[6:7] op_sel_hi:[1,0]
	v_cvt_pk_bf16_f32 v9, v10, v11
	global_store_dwordx2 v[48:49], v[8:9], off offset:128
	s_waitcnt vmcnt(3)
	v_mov_b64_e32 v[8:9], v[150:151]
	v_mov_b64_e32 v[10:11], v[152:153]
	global_load_dwordx4 v[150:153], v[118:119], off offset:352
	v_pk_mul_f32 v[8:9], v[12:13], v[8:9]
	v_pk_mul_f32 v[12:13], v[32:33], v[6:7] op_sel_hi:[1,0]
	v_cvt_pk_bf16_f32 v8, v8, v9
	v_pk_mul_f32 v[10:11], v[12:13], v[10:11]
	v_pk_mul_f32 v[12:13], v[26:27], v[6:7] op_sel_hi:[1,0]
	v_cvt_pk_bf16_f32 v9, v10, v11
	global_store_dwordx2 v[48:49], v[8:9], off offset:144
	s_waitcnt vmcnt(3)
	v_mov_b64_e32 v[8:9], v[192:193]
	v_mov_b64_e32 v[10:11], v[194:195]
	global_load_dwordx4 v[192:195], v[118:119], off offset:384
	v_pk_mul_f32 v[8:9], v[12:13], v[8:9]
	v_pk_mul_f32 v[12:13], v[22:23], v[6:7] op_sel_hi:[1,0]
	v_cvt_pk_bf16_f32 v8, v8, v9
	v_pk_mul_f32 v[10:11], v[12:13], v[10:11]
	v_pk_mul_f32 v[12:13], v[24:25], v[6:7] op_sel_hi:[1,0]
	v_cvt_pk_bf16_f32 v9, v10, v11
	global_store_dwordx2 v[48:49], v[8:9], off offset:160
	s_waitcnt vmcnt(3)
	v_mov_b64_e32 v[8:9], v[150:151]
	v_mov_b64_e32 v[10:11], v[152:153]
	global_load_dwordx4 v[150:153], v[118:119], off offset:416
	v_pk_mul_f32 v[8:9], v[12:13], v[8:9]
	v_pk_mul_f32 v[12:13], v[20:21], v[6:7] op_sel_hi:[1,0]
	v_cvt_pk_bf16_f32 v8, v8, v9
	v_pk_mul_f32 v[10:11], v[12:13], v[10:11]
	v_pk_mul_f32 v[12:13], v[18:19], v[6:7] op_sel_hi:[1,0]
	v_cvt_pk_bf16_f32 v9, v10, v11
	global_store_dwordx2 v[48:49], v[8:9], off offset:176
	s_waitcnt vmcnt(3)
	v_mov_b64_e32 v[8:9], v[192:193]
	v_mov_b64_e32 v[10:11], v[194:195]
	global_load_dwordx4 v[192:195], v[118:119], off offset:448
	v_pk_mul_f32 v[8:9], v[12:13], v[8:9]
	v_pk_mul_f32 v[12:13], v[16:17], v[6:7] op_sel_hi:[1,0]
	v_cvt_pk_bf16_f32 v8, v8, v9
	v_pk_mul_f32 v[10:11], v[12:13], v[10:11]
	s_nop 0
	v_cvt_pk_bf16_f32 v9, v10, v11
	global_store_dwordx2 v[48:49], v[8:9], off offset:192
	s_waitcnt vmcnt(3)
	v_mov_b64_e32 v[8:9], v[150:151]
	v_mov_b64_e32 v[10:11], v[152:153]
	global_load_dwordx4 v[150:153], v[118:119], off offset:480
	v_pk_mul_f32 v[4:5], v[4:5], v[8:9]
	v_pk_mul_f32 v[2:3], v[2:3], v[10:11]
	v_cvt_pk_bf16_f32 v4, v4, v5
	v_cvt_pk_bf16_f32 v5, v2, v3
	global_store_dwordx2 v[48:49], v[4:5], off offset:208
	s_waitcnt vmcnt(3)
	v_mov_b64_e32 v[2:3], v[192:193]
	v_mov_b64_e32 v[4:5], v[194:195]
	v_pk_mul_f32 v[0:1], v[0:1], v[2:3]
	v_pk_mul_f32 v[2:3], v[64:65], v[6:7] op_sel_hi:[1,0]
	v_cvt_pk_bf16_f32 v0, v0, v1
	v_pk_mul_f32 v[2:3], v[2:3], v[4:5]
	v_pk_mul_f32 v[4:5], v[66:67], v[6:7] op_sel_hi:[1,0]
	v_cvt_pk_bf16_f32 v1, v2, v3
	global_store_dwordx2 v[48:49], v[0:1], off offset:224
	s_waitcnt vmcnt(2)
	v_mov_b64_e32 v[0:1], v[150:151]
	v_mov_b64_e32 v[2:3], v[152:153]
	v_pk_mul_f32 v[0:1], v[4:5], v[0:1]
	v_pk_mul_f32 v[4:5], v[14:15], v[6:7] op_sel_hi:[1,0]
	v_cvt_pk_bf16_f32 v0, v0, v1
	v_pk_mul_f32 v[2:3], v[4:5], v[2:3]
	s_nop 0
	v_cvt_pk_bf16_f32 v1, v2, v3
	global_store_dwordx2 v[48:49], v[0:1], off offset:240

; DI void diff_attn_unit(int b, int h, int qb, const bf16_t* Z, const bf16_t* VT, bf16_t* H, float lam, const float* subg, float oscale, LAS unsigned char* lds, int wid, int lane) {
;     ...
;     __syncthreads();
;     if (mp == 0) { const float i0 = 1.0f / ls; float ss = 0.f;
; #pragma unroll
;         for (int d = 0; d < 4; ++d)
; #pragma unroll
;             for (int i = 0; i < 16; ++i) { const float o = O[d][i] * i0 - xch[(d * 16 + i) * 64 + lane]; O[d][i] = o; ss += o * o; }
.LBB0_2235:
	s_and_b64 vcc, exec, s[2:3]
	s_waitcnt lgkmcnt(0)
	s_barrier
	s_cbranch_vccnz .LBB0_2216
	v_div_scale_f32 v65, s[2:3], v64, v64, 1.0
	v_rcp_f32_e32 v66, v65
	v_mov_b32_e32 v139, v97
	v_fma_f32 v67, -v65, v66, 1.0
	v_fmac_f32_e32 v66, v67, v66
	v_div_scale_f32 v67, vcc, 1.0, v64, 1.0
	v_mul_f32_e32 v68, v67, v66
	v_fma_f32 v69, -v65, v68, v67
	v_fmac_f32_e32 v68, v69, v66
	v_fma_f32 v65, -v65, v68, v67
	v_div_fmas_f32 v65, v65, v66, v68
	v_div_fixup_f32 v68, v65, v64, 1.0
	ds_read2st64_b32 v[80:81], v188 offset1:1
	ds_read2st64_b32 v[72:73], v188 offset0:2 offset1:3
	ds_read2st64_b32 v[94:95], v188 offset0:4 offset1:5
	ds_read2st64_b32 v[86:87], v188 offset0:6 offset1:7
	ds_read2st64_b32 v[98:99], v188 offset0:8 offset1:9
	ds_read2st64_b32 v[134:135], v188 offset0:10 offset1:11
	ds_read2st64_b32 v[136:137], v188 offset0:12 offset1:13
	ds_read2st64_b32 v[140:141], v188 offset0:14 offset1:15
	ds_read2st64_b32 v[142:143], v188 offset0:16 offset1:17
	ds_read2st64_b32 v[144:145], v188 offset0:18 offset1:19
	ds_read2st64_b32 v[146:147], v188 offset0:20 offset1:21
	ds_read2st64_b32 v[150:151], v188 offset0:22 offset1:23
	ds_read2st64_b32 v[152:153], v188 offset0:24 offset1:25
	ds_read2st64_b32 v[162:163], v188 offset0:26 offset1:27
	ds_read2st64_b32 v[130:131], v188 offset0:28 offset1:29
	ds_read2st64_b32 v[164:165], v188 offset0:30 offset1:31
	ds_read2st64_b32 v[108:109], v188 offset0:32 offset1:33
	ds_read2st64_b32 v[132:133], v188 offset0:34 offset1:35
	ds_read2st64_b32 v[104:105], v188 offset0:36 offset1:37
	ds_read2st64_b32 v[110:111], v188 offset0:38 offset1:39
	ds_read2st64_b32 v[100:101], v188 offset0:40 offset1:41
	ds_read2st64_b32 v[106:107], v188 offset0:42 offset1:43
	ds_read2st64_b32 v[92:93], v188 offset0:44 offset1:45
	ds_read2st64_b32 v[102:103], v188 offset0:46 offset1:47
	ds_read2st64_b32 v[88:89], v188 offset0:48 offset1:49
	ds_read2st64_b32 v[90:91], v188 offset0:50 offset1:51
	ds_read2st64_b32 v[78:79], v188 offset0:52 offset1:53
	ds_read2st64_b32 v[84:85], v188 offset0:54 offset1:55
	ds_read2st64_b32 v[74:75], v188 offset0:56 offset1:57
	ds_read2st64_b32 v[64:65], v188 offset0:58 offset1:59
	s_waitcnt lgkmcnt(14)
	v_pk_fma_f32 v[82:83], v[48:49], v[68:69], v[80:81] op_sel_hi:[1,0,1] neg_lo:[0,0,1] neg_hi:[0,0,1]
	v_pk_fma_f32 v[72:73], v[50:51], v[68:69], v[72:73] op_sel_hi:[1,0,1] neg_lo:[0,0,1] neg_hi:[0,0,1]
	v_pk_mul_f32 v[168:169], v[82:83], v[82:83]
	v_pk_mul_f32 v[166:167], v[72:73], v[72:73]
	s_waitcnt lgkmcnt(0)
	v_pk_fma_f32 v[64:65], v[10:11], v[68:69], v[64:65] op_sel_hi:[1,0,1] neg_lo:[0,0,1] neg_hi:[0,0,1]
	ds_read2st64_b32 v[10:11], v188 offset0:60 offset1:61
	v_pk_fma_f32 v[86:87], v[54:55], v[68:69], v[86:87] op_sel_hi:[1,0,1] neg_lo:[0,0,1] neg_hi:[0,0,1]
	v_pk_fma_f32 v[94:95], v[52:53], v[68:69], v[94:95] op_sel_hi:[1,0,1] neg_lo:[0,0,1] neg_hi:[0,0,1]
	v_pk_fma_f32 v[80:81], v[58:59], v[68:69], v[134:135] op_sel_hi:[1,0,1] neg_lo:[0,0,1] neg_hi:[0,0,1]
	v_pk_fma_f32 v[98:99], v[56:57], v[68:69], v[98:99] op_sel_hi:[1,0,1] neg_lo:[0,0,1] neg_hi:[0,0,1]
	s_waitcnt lgkmcnt(0)
	v_pk_fma_f32 v[66:67], v[12:13], v[68:69], v[10:11] op_sel_hi:[1,0,1] neg_lo:[0,0,1] neg_hi:[0,0,1]
	ds_read2st64_b32 v[10:11], v188 offset0:62 offset1:63
	v_pk_fma_f32 v[62:63], v[62:63], v[68:69], v[140:141] op_sel_hi:[1,0,1] neg_lo:[0,0,1] neg_hi:[0,0,1]
	v_pk_fma_f32 v[60:61], v[60:61], v[68:69], v[136:137] op_sel_hi:[1,0,1] neg_lo:[0,0,1] neg_hi:[0,0,1]
	v_pk_fma_f32 v[56:57], v[34:35], v[68:69], v[144:145] op_sel_hi:[1,0,1] neg_lo:[0,0,1] neg_hi:[0,0,1]
	v_pk_fma_f32 v[58:59], v[32:33], v[68:69], v[142:143] op_sel_hi:[1,0,1] neg_lo:[0,0,1] neg_hi:[0,0,1]
	s_waitcnt lgkmcnt(0)
	v_pk_fma_f32 v[14:15], v[14:15], v[68:69], v[10:11] op_sel_hi:[1,0,1] neg_lo:[0,0,1] neg_hi:[0,0,1]
	v_lshlrev_b64 v[10:11], 11, v[148:149]
	v_lshl_add_u64 v[10:11], s[48:49], 0, v[10:11]
	v_pk_fma_f32 v[50:51], v[38:39], v[68:69], v[150:151] op_sel_hi:[1,0,1] neg_lo:[0,0,1] neg_hi:[0,0,1]
	v_pk_fma_f32 v[54:55], v[36:37], v[68:69], v[146:147] op_sel_hi:[1,0,1] neg_lo:[0,0,1] neg_hi:[0,0,1]
	v_pk_fma_f32 v[42:43], v[42:43], v[68:69], v[162:163] op_sel_hi:[1,0,1] neg_lo:[0,0,1] neg_hi:[0,0,1]
	v_pk_fma_f32 v[52:53], v[40:41], v[68:69], v[152:153] op_sel_hi:[1,0,1] neg_lo:[0,0,1] neg_hi:[0,0,1]
	v_pk_fma_f32 v[40:41], v[46:47], v[68:69], v[164:165] op_sel_hi:[1,0,1] neg_lo:[0,0,1] neg_hi:[0,0,1]
	v_pk_fma_f32 v[44:45], v[44:45], v[68:69], v[130:131] op_sel_hi:[1,0,1] neg_lo:[0,0,1] neg_hi:[0,0,1]
	v_pk_fma_f32 v[36:37], v[18:19], v[68:69], v[132:133] op_sel_hi:[1,0,1] neg_lo:[0,0,1] neg_hi:[0,0,1]
	v_pk_fma_f32 v[38:39], v[16:17], v[68:69], v[108:109] op_sel_hi:[1,0,1] neg_lo:[0,0,1] neg_hi:[0,0,1]
	v_pk_fma_f32 v[32:33], v[22:23], v[68:69], v[110:111] op_sel_hi:[1,0,1] neg_lo:[0,0,1] neg_hi:[0,0,1]
	v_pk_fma_f32 v[34:35], v[20:21], v[68:69], v[104:105] op_sel_hi:[1,0,1] neg_lo:[0,0,1] neg_hi:[0,0,1]
	v_pk_fma_f32 v[22:23], v[26:27], v[68:69], v[106:107] op_sel_hi:[1,0,1] neg_lo:[0,0,1] neg_hi:[0,0,1]
	v_pk_fma_f32 v[26:27], v[24:25], v[68:69], v[100:101] op_sel_hi:[1,0,1] neg_lo:[0,0,1] neg_hi:[0,0,1]
	v_pk_fma_f32 v[20:21], v[30:31], v[68:69], v[102:103] op_sel_hi:[1,0,1] neg_lo:[0,0,1] neg_hi:[0,0,1]
	v_pk_fma_f32 v[24:25], v[28:29], v[68:69], v[92:93] op_sel_hi:[1,0,1] neg_lo:[0,0,1] neg_hi:[0,0,1]
	v_pk_fma_f32 v[16:17], v[2:3], v[68:69], v[90:91] op_sel_hi:[1,0,1] neg_lo:[0,0,1] neg_hi:[0,0,1]
	v_pk_fma_f32 v[18:19], v[0:1], v[68:69], v[88:89] op_sel_hi:[1,0,1] neg_lo:[0,0,1] neg_hi:[0,0,1]
	v_pk_fma_f32 v[2:3], v[6:7], v[68:69], v[84:85] op_sel_hi:[1,0,1] neg_lo:[0,0,1] neg_hi:[0,0,1]
	v_pk_fma_f32 v[4:5], v[4:5], v[68:69], v[78:79] op_sel_hi:[1,0,1] neg_lo:[0,0,1] neg_hi:[0,0,1]
; DI unsigned pk2(float lo, float hi) { f32x2 v = {lo, hi}; bf16x2_t b = __builtin_convertvector(v, bf16x2_t); return __builtin_bit_cast(unsigned, b); }
; DI float rstd_of(float ssq, float inv_n) { return 1.0f / sqrtf(ssq * inv_n + EPS); }
; DI void diff_attn_unit(int b, int h, int qb, const bf16_t* Z, const bf16_t* VT, bf16_t* H, float lam, const float* subg, float oscale, LAS unsigned char* lds, int wid, int lane) {
;     ...
;             for (int i = 0; i < 16; ++i) { const float o = O[d][i] * i0 - xch[(d * 16 + i) * 64 + lane]; O[d][i] = o; ss += o * o; }
;         ss += __shfl_xor(ss, 32);
;         const float rs = rstd_of(ss, 1.0f / 128.f) * oscale;
;         bf16_t* hp = H + (size_t)qrow * DM + h * 128;
; #pragma unroll
;         for (int d = 0; d < 4; ++d)
; #pragma unroll
;             for (int rg = 0; rg < 4; ++rg) { const int d0 = 32 * d + 8 * rg + 4 * hi; const f32x4 g4 = *(const f32x4*)(subg + d0);
;                 u32x2 o; o.x = pk2(O[d][4 * rg] * rs * g4[0], O[d][4 * rg + 1] * rs * g4[1]); o.y = pk2(O[d][4 * rg + 2] * rs * g4[2], O[d][4 * rg + 3] * rs * g4[3]);
;                 *(u32x2*)(hp + d0) = o; } }
	v_pk_fma_f32 v[0:1], v[8:9], v[68:69], v[74:75] op_sel_hi:[1,0,1] neg_lo:[0,0,1] neg_hi:[0,0,1]
	v_add_f32_e32 v68, v168, v169
	v_lshl_add_u64 v[148:149], v[10:11], 0, s[6:7]
	v_add_f32_e32 v68, v68, v166
	v_lshl_add_u64 v[48:49], v[148:149], 0, v[138:139]
	v_pk_mul_f32 v[148:149], v[94:95], v[94:95]
	v_add_f32_e32 v68, v68, v167
	v_add_f32_e32 v68, v68, v148
	v_pk_mul_f32 v[138:139], v[86:87], v[86:87]
	v_add_f32_e32 v68, v68, v149
	v_add_f32_e32 v68, v68, v138
	v_pk_mul_f32 v[192:193], v[98:99], v[98:99]
	v_add_f32_e32 v68, v68, v139
	v_add_f32_e32 v68, v68, v192
	v_pk_mul_f32 v[134:135], v[80:81], v[80:81]
	v_add_f32_e32 v68, v68, v193
	v_add_f32_e32 v68, v68, v134
	v_pk_mul_f32 v[136:137], v[60:61], v[60:61]
	v_add_f32_e32 v68, v68, v135
	v_add_f32_e32 v68, v68, v136
	v_pk_mul_f32 v[140:141], v[62:63], v[62:63]
	v_add_f32_e32 v68, v68, v137
	v_add_f32_e32 v68, v68, v140
	v_pk_mul_f32 v[142:143], v[58:59], v[58:59]
	v_add_f32_e32 v68, v68, v141
	v_add_f32_e32 v68, v68, v142
	v_pk_mul_f32 v[144:145], v[56:57], v[56:57]
	v_add_f32_e32 v68, v68, v143
	v_add_f32_e32 v68, v68, v144
	v_pk_mul_f32 v[146:147], v[54:55], v[54:55]
	v_add_f32_e32 v68, v68, v145
	v_add_f32_e32 v68, v68, v146
	global_load_dwordx4 v[10:13], v[118:119], off
	global_load_dwordx4 v[140:143], v[118:119], off offset:32
	global_load_dwordx4 v[192:195], v[118:119], off offset:64
	v_pk_mul_f32 v[150:151], v[50:51], v[50:51]
	v_add_f32_e32 v68, v68, v147
	v_add_f32_e32 v68, v68, v150
	v_pk_mul_f32 v[152:153], v[52:53], v[52:53]
	v_add_f32_e32 v68, v68, v151
	v_add_f32_e32 v68, v68, v152
	v_pk_mul_f32 v[162:163], v[42:43], v[42:43]
	v_add_f32_e32 v68, v68, v153
	v_add_f32_e32 v68, v68, v162
	v_pk_mul_f32 v[130:131], v[44:45], v[44:45]
	v_add_f32_e32 v68, v68, v163
	v_add_f32_e32 v68, v68, v130
	v_pk_mul_f32 v[46:47], v[40:41], v[40:41]
	v_add_f32_e32 v68, v68, v131
	v_add_f32_e32 v46, v68, v46
	v_pk_mul_f32 v[108:109], v[38:39], v[38:39]
	v_add_f32_e32 v46, v46, v47
	v_add_f32_e32 v46, v46, v108
	v_pk_mul_f32 v[132:133], v[36:37], v[36:37]
	v_add_f32_e32 v46, v46, v109
	v_add_f32_e32 v46, v46, v132
	v_pk_mul_f32 v[104:105], v[34:35], v[34:35]
	v_add_f32_e32 v46, v46, v133
	v_add_f32_e32 v46, v46, v104
	v_pk_mul_f32 v[110:111], v[32:33], v[32:33]
	v_add_f32_e32 v46, v46, v105
	v_add_f32_e32 v46, v46, v110
	v_pk_mul_f32 v[100:101], v[26:27], v[26:27]
	v_add_f32_e32 v46, v46, v111
	v_add_f32_e32 v46, v46, v100
	v_pk_mul_f32 v[106:107], v[22:23], v[22:23]
	v_add_f32_e32 v46, v46, v101
	v_add_f32_e32 v46, v46, v106
	v_pk_mul_f32 v[28:29], v[24:25], v[24:25]
	v_add_f32_e32 v46, v46, v107
	v_add_f32_e32 v28, v46, v28
	v_pk_mul_f32 v[30:31], v[20:21], v[20:21]
	v_add_f32_e32 v28, v28, v29
	v_add_f32_e32 v28, v28, v30
	v_pk_mul_f32 v[88:89], v[18:19], v[18:19]
	v_add_f32_e32 v28, v28, v31
	v_add_f32_e32 v28, v28, v88
	v_pk_mul_f32 v[90:91], v[16:17], v[16:17]
	v_add_f32_e32 v28, v28, v89
	v_add_f32_e32 v28, v28, v90
	v_pk_mul_f32 v[78:79], v[4:5], v[4:5]
	v_add_f32_e32 v28, v28, v91
	v_add_f32_e32 v28, v28, v78
	v_pk_mul_f32 v[6:7], v[2:3], v[2:3]
	v_add_f32_e32 v28, v28, v79
	v_add_f32_e32 v6, v28, v6
	v_pk_mul_f32 v[8:9], v[0:1], v[0:1]
	v_add_f32_e32 v6, v6, v7
	v_add_f32_e32 v6, v6, v8
	v_pk_mul_f32 v[70:71], v[64:65], v[64:65]
	v_add_f32_e32 v6, v6, v9
	v_add_f32_e32 v6, v6, v70
	v_pk_mul_f32 v[76:77], v[66:67], v[66:67]
	v_add_f32_e32 v6, v6, v71
	v_add_f32_e32 v6, v6, v76
	v_pk_mul_f32 v[112:113], v[14:15], v[14:15]
	v_add_f32_e32 v6, v6, v77
	v_add_f32_e32 v6, v6, v112
	v_add_f32_e32 v6, v6, v113
	ds_bpermute_b32 v7, v208, v6
	s_waitcnt lgkmcnt(0)
	v_add_f32_e32 v6, v6, v7
	v_fmamk_f32 v6, v6, 0x3c000000, v222
	v_rsq_f32_e32 v8, v6
	s_nop 0
	v_mul_f32_e32 v7, v6, v8
	v_fma_f32 v7, -v7, v8, 1.0
	v_mul_f32_e32 v7, 0.5, v7
	v_fma_f32 v6, v7, v8, v8
	v_mul_f32_e32 v6, v174, v6
	v_pk_mul_f32 v[8:9], v[82:83], v[6:7] op_sel_hi:[1,0]
	v_pk_mul_f32 v[4:5], v[4:5], v[6:7] op_sel_hi:[1,0]
	s_waitcnt vmcnt(0)
	v_pk_mul_f32 v[8:9], v[10:11], v[8:9]
	v_pk_mul_f32 v[10:11], v[72:73], v[6:7] op_sel_hi:[1,0]
	v_cvt_pk_bf16_f32 v8, v8, v9
	v_pk_mul_f32 v[10:11], v[12:13], v[10:11]
	v_pk_mul_f32 v[12:13], v[94:95], v[6:7] op_sel_hi:[1,0]
	v_cvt_pk_bf16_f32 v9, v10, v11
	global_store_dwordx2 v[48:49], v[8:9], off
	v_pk_mul_f32 v[2:3], v[2:3], v[6:7] op_sel_hi:[1,0]
	v_pk_mul_f32 v[0:1], v[0:1], v[6:7] op_sel_hi:[1,0]
	s_waitcnt vmcnt(2)
	v_mov_b64_e32 v[8:9], v[140:141]
	v_mov_b64_e32 v[10:11], v[142:143]
	global_load_dwordx4 v[140:143], v[118:119], off offset:96
	v_pk_mul_f32 v[8:9], v[8:9], v[12:13]
	v_pk_mul_f32 v[12:13], v[86:87], v[6:7] op_sel_hi:[1,0]
	v_cvt_pk_bf16_f32 v8, v8, v9
	v_pk_mul_f32 v[10:11], v[10:11], v[12:13]
	v_pk_mul_f32 v[12:13], v[98:99], v[6:7] op_sel_hi:[1,0]
	v_cvt_pk_bf16_f32 v9, v10, v11
	global_store_dwordx2 v[48:49], v[8:9], off offset:16
	s_waitcnt vmcnt(3)
	v_mov_b64_e32 v[8:9], v[192:193]
	v_mov_b64_e32 v[10:11], v[194:195]
	global_load_dwordx4 v[192:195], v[118:119], off offset:128
	v_pk_mul_f32 v[8:9], v[8:9], v[12:13]
	v_pk_mul_f32 v[12:13], v[80:81], v[6:7] op_sel_hi:[1,0]
	v_cvt_pk_bf16_f32 v8, v8, v9
	v_pk_mul_f32 v[10:11], v[10:11], v[12:13]
	v_pk_mul_f32 v[12:13], v[60:61], v[6:7] op_sel_hi:[1,0]
	v_cvt_pk_bf16_f32 v9, v10, v11
	global_store_dwordx2 v[48:49], v[8:9], off offset:32
	s_waitcnt vmcnt(3)
; DI unsigned pk2(float lo, float hi) { f32x2 v = {lo, hi}; bf16x2_t b = __builtin_convertvector(v, bf16x2_t); return __builtin_bit_cast(unsigned, b); }
; DI void diff_attn_unit(int b, int h, int qb, const bf16_t* Z, const bf16_t* VT, bf16_t* H, float lam, const float* subg, float oscale, LAS unsigned char* lds, int wid, int lane) {
;     ...
;         for (int d = 0; d < 4; ++d)
; #pragma unroll
;             for (int rg = 0; rg < 4; ++rg) { const int d0 = 32 * d + 8 * rg + 4 * hi; const f32x4 g4 = *(const f32x4*)(subg + d0);
;                 u32x2 o; o.x = pk2(O[d][4 * rg] * rs * g4[0], O[d][4 * rg + 1] * rs * g4[1]); o.y = pk2(O[d][4 * rg + 2] * rs * g4[2], O[d][4 * rg + 3] * rs * g4[3]);
;                 *(u32x2*)(hp + d0) = o; } }
	v_mov_b64_e32 v[8:9], v[140:141]
	v_mov_b64_e32 v[10:11], v[142:143]
	global_load_dwordx4 v[140:143], v[118:119], off offset:160
	v_pk_mul_f32 v[8:9], v[8:9], v[12:13]
	v_pk_mul_f32 v[12:13], v[62:63], v[6:7] op_sel_hi:[1,0]
	v_cvt_pk_bf16_f32 v8, v8, v9
	v_pk_mul_f32 v[10:11], v[10:11], v[12:13]
	v_pk_mul_f32 v[12:13], v[58:59], v[6:7] op_sel_hi:[1,0]
	v_cvt_pk_bf16_f32 v9, v10, v11
	global_store_dwordx2 v[48:49], v[8:9], off offset:48
	s_waitcnt vmcnt(3)
	v_mov_b64_e32 v[8:9], v[192:193]
	v_mov_b64_e32 v[10:11], v[194:195]
	global_load_dwordx4 v[192:195], v[118:119], off offset:192
	v_pk_mul_f32 v[8:9], v[8:9], v[12:13]
	v_pk_mul_f32 v[12:13], v[56:57], v[6:7] op_sel_hi:[1,0]
	v_cvt_pk_bf16_f32 v8, v8, v9
	v_pk_mul_f32 v[10:11], v[10:11], v[12:13]
	v_pk_mul_f32 v[12:13], v[54:55], v[6:7] op_sel_hi:[1,0]
	v_cvt_pk_bf16_f32 v9, v10, v11
	global_store_dwordx2 v[48:49], v[8:9], off offset:64
	s_waitcnt vmcnt(3)
	v_mov_b64_e32 v[8:9], v[140:141]
	v_mov_b64_e32 v[10:11], v[142:143]
	global_load_dwordx4 v[140:143], v[118:119], off offset:224
	v_pk_mul_f32 v[8:9], v[12:13], v[8:9]
	v_pk_mul_f32 v[12:13], v[50:51], v[6:7] op_sel_hi:[1,0]
	v_cvt_pk_bf16_f32 v8, v8, v9
	v_pk_mul_f32 v[10:11], v[12:13], v[10:11]
	v_pk_mul_f32 v[12:13], v[52:53], v[6:7] op_sel_hi:[1,0]
	v_cvt_pk_bf16_f32 v9, v10, v11
	global_store_dwordx2 v[48:49], v[8:9], off offset:80
	s_waitcnt vmcnt(3)
	v_mov_b64_e32 v[8:9], v[192:193]
	v_mov_b64_e32 v[10:11], v[194:195]
	global_load_dwordx4 v[192:195], v[118:119], off offset:256
	v_pk_mul_f32 v[8:9], v[12:13], v[8:9]
	v_pk_mul_f32 v[12:13], v[42:43], v[6:7] op_sel_hi:[1,0]
	v_cvt_pk_bf16_f32 v8, v8, v9
	v_pk_mul_f32 v[10:11], v[12:13], v[10:11]
	v_pk_mul_f32 v[12:13], v[44:45], v[6:7] op_sel_hi:[1,0]
	v_cvt_pk_bf16_f32 v9, v10, v11
	global_store_dwordx2 v[48:49], v[8:9], off offset:96
	s_waitcnt vmcnt(3)
	v_mov_b64_e32 v[8:9], v[140:141]
	v_mov_b64_e32 v[10:11], v[142:143]
	global_load_dwordx4 v[140:143], v[118:119], off offset:288
	v_pk_mul_f32 v[8:9], v[12:13], v[8:9]
	v_pk_mul_f32 v[12:13], v[40:41], v[6:7] op_sel_hi:[1,0]
	v_cvt_pk_bf16_f32 v8, v8, v9
	v_pk_mul_f32 v[10:11], v[12:13], v[10:11]
	v_pk_mul_f32 v[12:13], v[38:39], v[6:7] op_sel_hi:[1,0]
	v_cvt_pk_bf16_f32 v9, v10, v11
	global_store_dwordx2 v[48:49], v[8:9], off offset:112
	s_waitcnt vmcnt(3)
	v_mov_b64_e32 v[8:9], v[192:193]
	v_mov_b64_e32 v[10:11], v[194:195]
	global_load_dwordx4 v[192:195], v[118:119], off offset:320
	v_pk_mul_f32 v[8:9], v[12:13], v[8:9]
	v_pk_mul_f32 v[12:13], v[36:37], v[6:7] op_sel_hi:[1,0]
	v_cvt_pk_bf16_f32 v8, v8, v9
	v_pk_mul_f32 v[10:11], v[12:13], v[10:11]
	v_pk_mul_f32 v[12:13], v[34:35], v[6:7] op_sel_hi:[1,0]
	v_cvt_pk_bf16_f32 v9, v10, v11
	global_store_dwordx2 v[48:49], v[8:9], off offset:128
	s_waitcnt vmcnt(3)
	v_mov_b64_e32 v[8:9], v[140:141]
	v_mov_b64_e32 v[10:11], v[142:143]
	global_load_dwordx4 v[140:143], v[118:119], off offset:352
	v_pk_mul_f32 v[8:9], v[12:13], v[8:9]
	v_pk_mul_f32 v[12:13], v[32:33], v[6:7] op_sel_hi:[1,0]
	v_cvt_pk_bf16_f32 v8, v8, v9
	v_pk_mul_f32 v[10:11], v[12:13], v[10:11]
	v_pk_mul_f32 v[12:13], v[26:27], v[6:7] op_sel_hi:[1,0]
	v_cvt_pk_bf16_f32 v9, v10, v11
	global_store_dwordx2 v[48:49], v[8:9], off offset:144
	s_waitcnt vmcnt(3)
	v_mov_b64_e32 v[8:9], v[192:193]
	v_mov_b64_e32 v[10:11], v[194:195]
	global_load_dwordx4 v[192:195], v[118:119], off offset:384
	v_pk_mul_f32 v[8:9], v[12:13], v[8:9]
	v_pk_mul_f32 v[12:13], v[22:23], v[6:7] op_sel_hi:[1,0]
	v_cvt_pk_bf16_f32 v8, v8, v9
	v_pk_mul_f32 v[10:11], v[12:13], v[10:11]
	v_pk_mul_f32 v[12:13], v[24:25], v[6:7] op_sel_hi:[1,0]
	v_cvt_pk_bf16_f32 v9, v10, v11
	global_store_dwordx2 v[48:49], v[8:9], off offset:160
	s_waitcnt vmcnt(3)
	v_mov_b64_e32 v[8:9], v[140:141]
	v_mov_b64_e32 v[10:11], v[142:143]
	global_load_dwordx4 v[140:143], v[118:119], off offset:416
	v_pk_mul_f32 v[8:9], v[12:13], v[8:9]
	v_pk_mul_f32 v[12:13], v[20:21], v[6:7] op_sel_hi:[1,0]
	v_cvt_pk_bf16_f32 v8, v8, v9
	v_pk_mul_f32 v[10:11], v[12:13], v[10:11]
	v_pk_mul_f32 v[12:13], v[18:19], v[6:7] op_sel_hi:[1,0]
	v_cvt_pk_bf16_f32 v9, v10, v11
	global_store_dwordx2 v[48:49], v[8:9], off offset:176
	s_waitcnt vmcnt(3)
	v_mov_b64_e32 v[8:9], v[192:193]
	v_mov_b64_e32 v[10:11], v[194:195]
	global_load_dwordx4 v[192:195], v[118:119], off offset:448
	v_pk_mul_f32 v[8:9], v[12:13], v[8:9]
	v_pk_mul_f32 v[12:13], v[16:17], v[6:7] op_sel_hi:[1,0]
	v_cvt_pk_bf16_f32 v8, v8, v9
	v_pk_mul_f32 v[10:11], v[12:13], v[10:11]
	s_nop 0
	v_cvt_pk_bf16_f32 v9, v10, v11
	global_store_dwordx2 v[48:49], v[8:9], off offset:192
	s_waitcnt vmcnt(3)
	v_mov_b64_e32 v[8:9], v[140:141]
	v_mov_b64_e32 v[10:11], v[142:143]
	global_load_dwordx4 v[140:143], v[118:119], off offset:480
	v_pk_mul_f32 v[4:5], v[4:5], v[8:9]
	v_pk_mul_f32 v[2:3], v[2:3], v[10:11]
	v_cvt_pk_bf16_f32 v4, v4, v5
	v_cvt_pk_bf16_f32 v5, v2, v3
	global_store_dwordx2 v[48:49], v[4:5], off offset:208
	s_waitcnt vmcnt(3)
	v_mov_b64_e32 v[2:3], v[192:193]
	v_mov_b64_e32 v[4:5], v[194:195]
	v_pk_mul_f32 v[0:1], v[0:1], v[2:3]
	v_pk_mul_f32 v[2:3], v[64:65], v[6:7] op_sel_hi:[1,0]
	v_cvt_pk_bf16_f32 v0, v0, v1
	v_pk_mul_f32 v[2:3], v[2:3], v[4:5]
	v_pk_mul_f32 v[4:5], v[66:67], v[6:7] op_sel_hi:[1,0]
	v_cvt_pk_bf16_f32 v1, v2, v3
	global_store_dwordx2 v[48:49], v[0:1], off offset:224
	s_waitcnt vmcnt(2)
	v_mov_b64_e32 v[0:1], v[140:141]
	v_mov_b64_e32 v[2:3], v[142:143]
	v_pk_mul_f32 v[0:1], v[4:5], v[0:1]
	v_pk_mul_f32 v[4:5], v[14:15], v[6:7] op_sel_hi:[1,0]
	v_cvt_pk_bf16_f32 v0, v0, v1
	v_pk_mul_f32 v[2:3], v[4:5], v[2:3]
	s_nop 0
	v_cvt_pk_bf16_f32 v1, v2, v3
	global_store_dwordx2 v[48:49], v[0:1], off offset:240
	s_branch .LBB0_2216

; DI float rstd_of(float ssq, float inv_n) { return 1.0f / sqrtf(ssq * inv_n + EPS); }
; DI void acc_add(acc_t* p, float v, float scale) { atomicAdd(p, (acc_t)(v * scale)); }
; DI float acc_get(const acc_t* p, float inv_scale) { return (float)(*p) * inv_scale; }
; DI float acc_get_i(const acc_t* base, unsigned idx, float inv_scale) { return (float)(*(const acc_t*)((const char*)base + idx * 8u)) * inv_scale; }
;     DI void operator()(const f32x4 (&acc)[2][2][4][2], const Unit& u, int wr, int wc, int fr, int fq) const {
;     ...
;             const int c4 = c8 + 4 * n;
;             const f32x4 w0 = *(const f32x4*)(cw + c4), w1 = *(const f32x4*)(cw + DFF + c4), w2 = *(const f32x4*)(cw + 2 * DFF + c4), cbv = *(const f32x4*)(cb + c4);
; #pragma unroll
;             for (int ai = 0; ai < 2; ++ai) {
;                 f32x4 pg = {0.f, 0.f, 0.f, 0.f};
; #pragma unroll
;                 for (int m = 0; m < 4; ++m) { const int row = u.pm * BM + ai * HALF + wr * 64 + m * 16 + fr;
;                     const float rs = rstd_of(acc_get_i(ssq, (unsigned)row, 1.0f / SSQ_SCALE), 1.0f / DM);
;                     const f32x4 g = acc[ai][0][m][n] * rs, up = acc[ai][1][m][n] * rs;
;                     f32x4 a;
; #pragma unroll
;                     for (int j = 0; j < 4; ++j) { const float s1 = __shfl(fr == 15 ? pg[j] : g[j], src1), s2 = __shfl(fr >= 14 ? pg[j] : g[j], src2);
.LBB0_3093:
	s_lshl_b32 s15, s0, 8
	s_add_i32 s15, s15, s80
	v_or_b32_e32 v194, s15, v209
	v_lshlrev_b32_e32 v96, 3, v194
	v_lshlrev_b64 v[142:143], 2, v[176:177]
	v_lshl_add_u64 v[178:179], s[54:55], 0, v[142:143]
	v_lshl_add_u64 v[134:135], s[62:63], 0, v[142:143]
	v_lshl_add_u64 v[138:139], s[64:65], 0, v[142:143]
	v_lshl_add_u64 v[180:181], s[56:57], 0, v[142:143]
	global_load_dwordx4 v[130:133], v[178:179], off
	global_load_dwordx4 v[142:145], v[180:181], off
	v_mul_lo_u32 v218, v194, s90
	global_load_dwordx4 v[134:137], v[134:135], off
	global_load_dwordx2 v[236:237], v96, s[48:49]
	global_load_dwordx2 v[238:239], v96, s[48:49] offset:128
	global_load_dwordx2 v[240:241], v96, s[48:49] offset:256
	global_load_dwordx2 v[242:243], v96, s[48:49] offset:384
	global_load_dwordx2 v[246:247], v96, s[48:49] offset:1024
	global_load_dwordx2 v[250:251], v96, s[48:49] offset:1152
	global_load_dwordx2 v[146:147], v96, s[48:49] offset:1280
	global_load_dwordx2 v[148:149], v96, s[48:49] offset:1408
	s_waitcnt vmcnt(0)
	v_ffbh_u32_e32 v150, v237
	v_min_u32_e32 v150, 32, v150
	v_lshlrev_b64 v[236:237], v150, v[236:237]
	v_min_u32_e32 v236, 1, v236
	v_or_b32_e32 v236, v237, v236
	v_cvt_f32_u32_e32 v236, v236
	v_sub_u32_e32 v237, 32, v150
	v_ldexp_f32 v236, v236, v237
	v_mul_f32_e32 v236, 0x35800000, v236
	v_fmamk_f32 v236, v236, 0x3a800000, v222
	v_rsq_f32_e32 v237, v236
	s_nop 0
	v_mul_f32_e32 v150, v236, v237
	v_fma_f32 v150, -v150, v237, 1.0
	v_mul_f32_e32 v150, 0.5, v150
	v_fmac_f32_e32 v237, v150, v237
	v_ffbh_u32_e32 v150, v239
	v_min_u32_e32 v150, 32, v150
	v_lshlrev_b64 v[238:239], v150, v[238:239]
	v_min_u32_e32 v238, 1, v238
	v_or_b32_e32 v238, v239, v238
	v_cvt_f32_u32_e32 v238, v238
	v_sub_u32_e32 v239, 32, v150
	v_ldexp_f32 v238, v238, v239
	v_mul_f32_e32 v238, 0x35800000, v238
	v_fmamk_f32 v238, v238, 0x3a800000, v222
	v_rsq_f32_e32 v239, v238
	s_nop 0
	v_mul_f32_e32 v150, v238, v239
	v_fma_f32 v150, -v150, v239, 1.0
	v_mul_f32_e32 v150, 0.5, v150
	v_fmac_f32_e32 v239, v150, v239
	v_ffbh_u32_e32 v150, v241
	v_min_u32_e32 v150, 32, v150
	v_lshlrev_b64 v[240:241], v150, v[240:241]
	v_min_u32_e32 v240, 1, v240
	v_or_b32_e32 v240, v241, v240
	v_cvt_f32_u32_e32 v240, v240
	v_sub_u32_e32 v241, 32, v150
	v_ldexp_f32 v240, v240, v241
	v_mul_f32_e32 v240, 0x35800000, v240
	v_fmamk_f32 v240, v240, 0x3a800000, v222
	v_rsq_f32_e32 v241, v240
	s_nop 0
	v_mul_f32_e32 v150, v240, v241
	v_fma_f32 v150, -v150, v241, 1.0
	v_mul_f32_e32 v150, 0.5, v150
	v_fmac_f32_e32 v241, v150, v241
	v_ffbh_u32_e32 v150, v243
	v_min_u32_e32 v150, 32, v150
	v_lshlrev_b64 v[242:243], v150, v[242:243]
	v_min_u32_e32 v242, 1, v242
	v_or_b32_e32 v242, v243, v242
	v_cvt_f32_u32_e32 v242, v242
	v_sub_u32_e32 v243, 32, v150
	v_ldexp_f32 v242, v242, v243
	v_mul_f32_e32 v242, 0x35800000, v242
	v_fmamk_f32 v242, v242, 0x3a800000, v222
	v_rsq_f32_e32 v243, v242
	s_nop 0
	v_mul_f32_e32 v150, v242, v243
	v_fma_f32 v150, -v150, v243, 1.0
	v_mul_f32_e32 v150, 0.5, v150
	v_fmac_f32_e32 v243, v150, v243
	v_ffbh_u32_e32 v150, v247
	v_min_u32_e32 v150, 32, v150
	v_lshlrev_b64 v[246:247], v150, v[246:247]
	v_min_u32_e32 v246, 1, v246
	v_or_b32_e32 v246, v247, v246
	v_cvt_f32_u32_e32 v246, v246
	v_sub_u32_e32 v247, 32, v150
	v_ldexp_f32 v246, v246, v247
	v_mul_f32_e32 v246, 0x35800000, v246
	v_fmamk_f32 v246, v246, 0x3a800000, v222
	v_rsq_f32_e32 v247, v246
	s_nop 0
	v_mul_f32_e32 v150, v246, v247
	v_fma_f32 v150, -v150, v247, 1.0
	v_mul_f32_e32 v150, 0.5, v150
	v_fmac_f32_e32 v247, v150, v247
	v_ffbh_u32_e32 v150, v251
	v_min_u32_e32 v150, 32, v150
	v_lshlrev_b64 v[250:251], v150, v[250:251]
	v_min_u32_e32 v250, 1, v250
	v_or_b32_e32 v250, v251, v250
	v_cvt_f32_u32_e32 v250, v250
	v_sub_u32_e32 v251, 32, v150
	v_ldexp_f32 v250, v250, v251
	v_mul_f32_e32 v250, 0x35800000, v250
	v_fmamk_f32 v250, v250, 0x3a800000, v222
	v_rsq_f32_e32 v251, v250
	s_nop 0
	v_mul_f32_e32 v150, v250, v251
	v_fma_f32 v150, -v150, v251, 1.0
	v_mul_f32_e32 v150, 0.5, v150
	v_fmac_f32_e32 v251, v150, v251
	v_ffbh_u32_e32 v150, v147
	v_min_u32_e32 v150, 32, v150
	v_lshlrev_b64 v[146:147], v150, v[146:147]
	v_min_u32_e32 v146, 1, v146
	v_or_b32_e32 v146, v147, v146
	v_cvt_f32_u32_e32 v146, v146
	v_sub_u32_e32 v147, 32, v150
	v_ldexp_f32 v146, v146, v147
	v_mul_f32_e32 v146, 0x35800000, v146
	v_fmamk_f32 v146, v146, 0x3a800000, v222
	v_rsq_f32_e32 v147, v146
	s_nop 0
	v_mul_f32_e32 v150, v146, v147
	v_fma_f32 v150, -v150, v147, 1.0
	v_mul_f32_e32 v150, 0.5, v150
	v_fmac_f32_e32 v147, v150, v147
	v_ffbh_u32_e32 v150, v149
	v_min_u32_e32 v150, 32, v150
	v_lshlrev_b64 v[148:149], v150, v[148:149]
	v_min_u32_e32 v148, 1, v148
	v_or_b32_e32 v148, v149, v148
	v_cvt_f32_u32_e32 v148, v148
	v_sub_u32_e32 v149, 32, v150
	v_ldexp_f32 v148, v148, v149
	v_mul_f32_e32 v148, 0x35800000, v148
	v_fmamk_f32 v148, v148, 0x3a800000, v222
	v_rsq_f32_e32 v149, v148
	s_nop 0
	v_mul_f32_e32 v150, v148, v149
	v_fma_f32 v150, -v150, v149, 1.0
	v_mul_f32_e32 v150, 0.5, v150
	v_fmac_f32_e32 v149, v150, v149
	v_mov_b32_e32 v236, v237
	v_mov_b32_e32 v237, v239
	v_mov_b32_e32 v238, v241
	v_mov_b32_e32 v239, v243
	v_mov_b32_e32 v240, v247
	v_mov_b32_e32 v241, v251
	v_mov_b32_e32 v242, v147
	v_mov_b32_e32 v243, v149
	s_waitcnt vmcnt(0)
	global_load_dwordx4 v[138:141], v[138:139], off
	v_mov_b32_e32 v148, v236
	v_pk_mul_f32 v[186:187], v[126:127], v[148:149] op_sel_hi:[1,0]
	v_pk_mul_f32 v[184:185], v[128:129], v[148:149] op_sel_hi:[1,0]
	v_cndmask_b32_e64 v150, v186, 0, s[36:37]
	ds_bpermute_b32 v188, v213, v150
	v_cndmask_b32_e64 v150, v186, 0, s[38:39]
	ds_bpermute_b32 v192, v214, v150
	v_cndmask_b32_e64 v150, v187, 0, s[36:37]
	ds_bpermute_b32 v189, v213, v150
	v_cndmask_b32_e64 v150, v187, 0, s[38:39]
	ds_bpermute_b32 v193, v214, v150
	v_cndmask_b32_e64 v150, v184, 0, s[36:37]
	ds_bpermute_b32 v182, v213, v150
	v_cndmask_b32_e64 v150, v184, 0, s[38:39]
	ds_bpermute_b32 v190, v214, v150
	v_cndmask_b32_e64 v150, v185, 0, s[36:37]
	ds_bpermute_b32 v183, v213, v150
	v_cndmask_b32_e64 v150, v185, 0, s[38:39]
	ds_bpermute_b32 v191, v214, v150
	v_pk_mul_f32 v[146:147], v[120:121], v[148:149] op_sel_hi:[1,0]
	v_pk_mul_f32 v[148:149], v[118:119], v[148:149] op_sel_hi:[1,0]
	s_and_saveexec_b64 s[0:1], s[40:41]
	s_xor_b64 s[0:1], exec, s[0:1]
	s_cbranch_execz .LBB0_3095
; DI unsigned pk2(float lo, float hi) { f32x2 v = {lo, hi}; bf16x2_t b = __builtin_convertvector(v, bf16x2_t); return __builtin_bit_cast(unsigned, b); }
; DI float silu_f(float x) { return x * __builtin_amdgcn_rcpf(1.f + __builtin_amdgcn_exp2f(-LOG2E * x)); }
; template <class T> DI T* boff(T* base, unsigned byte_off) { return (T*)((char*)base + byte_off); }
;     DI void operator()(const f32x4 (&acc)[2][2][4][2], const Unit& u, int wr, int wc, int fr, int fq) const {
;     ...
;                     for (int j = 0; j < 4; ++j) { const float s1 = __shfl(fr == 15 ? pg[j] : g[j], src1), s2 = __shfl(fr >= 14 ? pg[j] : g[j], src2);
;                         a[j] = silu_f(cbv[j] + w0[j] * s2 + w1[j] * s1 + w2[j] * g[j]) * up[j]; }
;                     u32x2 gw; gw.x = pk2(g[0], g[1]); gw.y = pk2(g[2], g[3]);
;                     if (m == 0 && fr < 2) {
;                         *boff((u32x2*)GS, (unsigned)(((row >> 6) * 4 + 2 + fr) * DFF + c4) * 2u) = gw;
;                         u32x2 uw; uw.x = pk2(up[0], up[1]); uw.y = pk2(up[2], up[3]); *boff((u32x2*)US, (unsigned)(((row >> 6) * 2 + fr) * DFF + c4) * 2u) = uw;
;                     } else { u32x2 w; w.x = pk2(a[0], a[1]); w.y = pk2(a[2], a[3]); *boff((u32x2*)A2, (unsigned)(row * DFF + c4) * 2u) = w; }
	s_waitcnt lgkmcnt(4)
	v_pk_fma_f32 v[150:151], v[130:131], v[192:193], v[142:143]
	s_nop 0
	v_pk_fma_f32 v[150:151], v[134:135], v[188:189], v[150:151]
	s_waitcnt lgkmcnt(0)
	v_pk_fma_f32 v[188:189], v[132:133], v[190:191], v[144:145]
	s_waitcnt vmcnt(0)
	v_pk_fma_f32 v[150:151], v[138:139], v[186:187], v[150:151]
	v_pk_fma_f32 v[182:183], v[136:137], v[182:183], v[188:189]
	v_mul_f32_e32 v152, 0xbfb8aa3b, v150
	v_mul_f32_e32 v153, 0xbfb8aa3b, v151
	v_pk_fma_f32 v[182:183], v[140:141], v[184:185], v[182:183]
	v_exp_f32_e32 v152, v152
	v_exp_f32_e32 v153, v153
	v_mul_f32_e32 v188, 0xbfb8aa3b, v182
	v_mul_f32_e32 v189, 0xbfb8aa3b, v183
	v_exp_f32_e32 v188, v188
	v_exp_f32_e32 v189, v189
	v_add_f32_e32 v152, 1.0, v152
	v_add_f32_e32 v153, 1.0, v153
	v_rcp_f32_e32 v152, v152
	v_rcp_f32_e32 v153, v153
	v_add_f32_e32 v188, 1.0, v188
	v_add_f32_e32 v189, 1.0, v189
	v_rcp_f32_e32 v188, v188
	v_rcp_f32_e32 v189, v189
	v_pk_mul_f32 v[150:151], v[150:151], v[152:153]
	s_nop 0
	v_pk_mul_f32 v[148:149], v[148:149], v[150:151]
	v_pk_mul_f32 v[150:151], v[182:183], v[188:189]
	v_cvt_pk_bf16_f32 v148, v148, v149
	v_pk_mul_f32 v[146:147], v[146:147], v[150:151]
	s_nop 0
	v_cvt_pk_bf16_f32 v149, v146, v147
	v_add_lshl_u32 v146, v218, v176, 1
	global_store_dwordx2 v146, v[148:149], s[46:47]
